# hand-written layer-0 weight conversion (64x64 tile per wave, no LDS, batched loads) + hand-written FoX cumulative gate scan
# speedup vs baseline: 1.2078x; 1.0185x over previous
; __device__ __forceinline__ float logsigf_(float x) { return fminf(x, 0.f) - log1pf(__expf(-fabsf(x))); }
; __device__ __forceinline__ void hyb_prep_phase(const Params& p, float* sm, int bid, int nb) {
;     ...
;   for (int item = bid; item < NB * 8; item += nb) {
;     const int b = item >> 3, h = item & 7;
;     const float bf = p.hyb_fox_bf[h];
;     const int p0 = tid * 33;
;     float x[33];
;     float s = 0.f;
; #pragma unroll
;     for (int i = 0; i < 33; i++) {
;       const int pr = p0 + i;
;       float lf = 0.f;
;       if (pr >= PADR && pr < LP) lf = logsigf_(zg[((size_t)b * LP + pr) * 16 + h] + bf);
;       x[i] = lf; s += lf;
;     }
.LBB0_2058:
	s_andn2_b64 vcc, exec, s[0:1]
	s_cbranch_vccnz .LBB0_2890
	v_readlane_b32 s0, v244, 26
	s_cmp_lt_i32 s0, 3
	s_mov_b64 s[0:1], -1
	s_cbranch_scc1 .LBB0_2543
	v_readlane_b32 s0, v244, 26
	s_cmp_lt_i32 s0, 4
	s_mov_b64 s[0:1], -1
	s_cbranch_scc1 .LBB0_2517
	v_readlane_b32 s0, v244, 26
	s_cmp_gt_i32 s0, 4
	s_mov_b64 s[0:1], -1
	s_cbranch_scc0 .LBB0_2181
	v_mov_b32_e32 v80, v2
	v_readlane_b32 s0, v244, 27
	v_and_b32_e32 v78, 63, v80
	s_mov_b32 s54, s28
	v_ashrrev_i32_e32 v79, 6, v80
	s_cmp_gt_i32 s0, 31
	v_cmp_eq_u32_e64 s[28:29], 0, v78
	v_cmp_gt_u32_e64 s[6:7], 4, v78
	s_cbranch_scc1 .LBB0_2165
	v_readlane_b32 s0, v244, 27
	v_readlane_b32 s8, v247, 3
	v_readlane_b32 s9, v247, 4
	v_readlane_b32 s12, v246, 45
	v_readlane_b32 s13, v246, 46
	s_lshr_b32 s1, s0, 3
	s_and_b32 s2, s0, 7
	s_add_u32 s10, s8, 0x19b88000
	s_addc_u32 s11, s9, 0
	s_add_u32 s8, s8, 0x19980000
	s_addc_u32 s9, s9, 0
	s_lshl_b32 s4, s2, 2
	v_mov_b32_e32 v70, s4
	v_mul_u32_u24_e32 v61, 33, v80
	s_mul_i32 s5, s1, 0x2080
	global_load_dword v60, v70, s[12:13]
	v_add_u32_e32 v63, s5, v61
	v_lshlrev_b32_e32 v63, 6, v63
	v_add_u32_e32 v63, s4, v63
	global_load_dword v10, v63, s[8:9]
	global_load_dword v11, v63, s[8:9] offset:64
	global_load_dword v12, v63, s[8:9] offset:128
	global_load_dword v13, v63, s[8:9] offset:192
	global_load_dword v14, v63, s[8:9] offset:256
	global_load_dword v15, v63, s[8:9] offset:320
	global_load_dword v16, v63, s[8:9] offset:384
	global_load_dword v17, v63, s[8:9] offset:448
	global_load_dword v18, v63, s[8:9] offset:512
	global_load_dword v19, v63, s[8:9] offset:576
	global_load_dword v20, v63, s[8:9] offset:640
	global_load_dword v21, v63, s[8:9] offset:704
	global_load_dword v22, v63, s[8:9] offset:768
	global_load_dword v23, v63, s[8:9] offset:832
	global_load_dword v24, v63, s[8:9] offset:896
	global_load_dword v25, v63, s[8:9] offset:960
	global_load_dword v26, v63, s[8:9] offset:1024
	global_load_dword v27, v63, s[8:9] offset:1088
	global_load_dword v28, v63, s[8:9] offset:1152
	global_load_dword v29, v63, s[8:9] offset:1216
	global_load_dword v30, v63, s[8:9] offset:1280
	global_load_dword v31, v63, s[8:9] offset:1344
	global_load_dword v32, v63, s[8:9] offset:1408
	global_load_dword v33, v63, s[8:9] offset:1472
	global_load_dword v34, v63, s[8:9] offset:1536
	global_load_dword v35, v63, s[8:9] offset:1600
	global_load_dword v36, v63, s[8:9] offset:1664
	global_load_dword v37, v63, s[8:9] offset:1728
	global_load_dword v38, v63, s[8:9] offset:1792
	global_load_dword v39, v63, s[8:9] offset:1856
	global_load_dword v40, v63, s[8:9] offset:1920
	global_load_dword v41, v63, s[8:9] offset:1984
	global_load_dword v42, v63, s[8:9] offset:2048
	s_mul_i32 s5, s0, 0x8200
	v_lshl_add_u32 v64, v61, 2, s5
	v_add_u32_e32 v65, 0xffffff90, v61
	v_sub_u32_e32 v66, 0x2080, v61
	s_mov_b32 s14, 0xbfb8aa3b
	s_mov_b32 s15, 0x2010
	s_waitcnt vmcnt(0)
	v_add_f32_e32 v10, v10, v60
	v_add_f32_e32 v11, v11, v60
	v_add_f32_e32 v12, v12, v60
	v_add_f32_e32 v13, v13, v60
	v_mul_f32_e64 v44, |v10|, s14
	v_mul_f32_e64 v48, |v11|, s14
	v_mul_f32_e64 v52, |v12|, s14
	v_mul_f32_e64 v56, |v13|, s14
	v_exp_f32_e32 v44, v44
	v_exp_f32_e32 v48, v48
	v_exp_f32_e32 v52, v52
	v_exp_f32_e32 v56, v56
	v_add_u32_e32 v47, 0, v65
	v_add_u32_e32 v51, 1, v65
	v_add_u32_e32 v55, 2, v65
	v_add_u32_e32 v59, 3, v65
	v_add_f32_e32 v45, 1.0, v44
	v_add_f32_e32 v49, 1.0, v48
	v_add_f32_e32 v53, 1.0, v52
	v_add_f32_e32 v57, 1.0, v56
	v_add_f32_e32 v46, -1.0, v45
	v_add_f32_e32 v50, -1.0, v49
	v_add_f32_e32 v54, -1.0, v53
	v_add_f32_e32 v58, -1.0, v57
	v_log_f32_e32 v45, v45
	v_log_f32_e32 v49, v49
	v_log_f32_e32 v53, v53
	v_log_f32_e32 v57, v57
	v_min_f32_e32 v10, 0, v10
	v_min_f32_e32 v11, 0, v11
	v_min_f32_e32 v12, 0, v12
	v_min_f32_e32 v13, 0, v13
	v_cmp_eq_f32_e32 vcc, 0, v46
	v_rcp_f32_e32 v46, v46
	v_mul_f32_e32 v45, 0x3f317218, v45
	s_nop 0
	v_mul_f32_e32 v46, v46, v44
	v_mul_f32_e32 v45, v45, v46
	v_cndmask_b32_e32 v45, v45, v44, vcc
	v_cmp_gt_u32_e32 vcc, s15, v47
	v_sub_f32_e32 v10, v10, v45
	s_nop 0
	v_cndmask_b32_e32 v10, 0, v10, vcc
	v_cmp_eq_f32_e32 vcc, 0, v50
	v_rcp_f32_e32 v50, v50
	v_mul_f32_e32 v49, 0x3f317218, v49
	s_nop 0
	v_mul_f32_e32 v50, v50, v48
	v_mul_f32_e32 v49, v49, v50
	v_cndmask_b32_e32 v49, v49, v48, vcc
	v_cmp_gt_u32_e32 vcc, s15, v51
	v_sub_f32_e32 v11, v11, v49
	s_nop 0
	v_cndmask_b32_e32 v11, 0, v11, vcc
	v_cmp_eq_f32_e32 vcc, 0, v54
	v_rcp_f32_e32 v54, v54
	v_mul_f32_e32 v53, 0x3f317218, v53
	s_nop 0
	v_mul_f32_e32 v54, v54, v52
	v_mul_f32_e32 v53, v53, v54
	v_cndmask_b32_e32 v53, v53, v52, vcc
	v_cmp_gt_u32_e32 vcc, s15, v55
	v_sub_f32_e32 v12, v12, v53
	s_nop 0
	v_cndmask_b32_e32 v12, 0, v12, vcc
	v_cmp_eq_f32_e32 vcc, 0, v58
	v_rcp_f32_e32 v58, v58
	v_mul_f32_e32 v57, 0x3f317218, v57
	s_nop 0
	v_mul_f32_e32 v58, v58, v56
	v_mul_f32_e32 v57, v57, v58
	v_cndmask_b32_e32 v57, v57, v56, vcc
	v_cmp_gt_u32_e32 vcc, s15, v59
	v_sub_f32_e32 v13, v13, v57
	s_nop 0
	v_cndmask_b32_e32 v13, 0, v13, vcc
	v_add_f32_e32 v14, v14, v60
	v_add_f32_e32 v15, v15, v60
	v_add_f32_e32 v16, v16, v60
	v_add_f32_e32 v17, v17, v60
	v_mul_f32_e64 v44, |v14|, s14
	v_mul_f32_e64 v48, |v15|, s14
	v_mul_f32_e64 v52, |v16|, s14
	v_mul_f32_e64 v56, |v17|, s14
	v_exp_f32_e32 v44, v44
	v_exp_f32_e32 v48, v48
	v_exp_f32_e32 v52, v52
	v_exp_f32_e32 v56, v56
	v_add_u32_e32 v47, 4, v65
	v_add_u32_e32 v51, 5, v65
	v_add_u32_e32 v55, 6, v65
	v_add_u32_e32 v59, 7, v65
	v_add_f32_e32 v45, 1.0, v44
	v_add_f32_e32 v49, 1.0, v48
	v_add_f32_e32 v53, 1.0, v52
	v_add_f32_e32 v57, 1.0, v56
	v_add_f32_e32 v46, -1.0, v45
	v_add_f32_e32 v50, -1.0, v49
	v_add_f32_e32 v54, -1.0, v53
	v_add_f32_e32 v58, -1.0, v57
; __device__ __forceinline__ float logsigf_(float x) { return fminf(x, 0.f) - log1pf(__expf(-fabsf(x))); }
; __device__ __forceinline__ void hyb_prep_phase(const Params& p, float* sm, int bid, int nb) {
;     ...
;     for (int i = 0; i < 33; i++) {
;       const int pr = p0 + i;
;       float lf = 0.f;
;       if (pr >= PADR && pr < LP) lf = logsigf_(zg[((size_t)b * LP + pr) * 16 + h] + bf);
;       x[i] = lf; s += lf;
;     }
	v_log_f32_e32 v45, v45
	v_log_f32_e32 v49, v49
	v_log_f32_e32 v53, v53
	v_log_f32_e32 v57, v57
	v_min_f32_e32 v14, 0, v14
	v_min_f32_e32 v15, 0, v15
	v_min_f32_e32 v16, 0, v16
	v_min_f32_e32 v17, 0, v17
	v_cmp_eq_f32_e32 vcc, 0, v46
	v_rcp_f32_e32 v46, v46
	v_mul_f32_e32 v45, 0x3f317218, v45
	s_nop 0
	v_mul_f32_e32 v46, v46, v44
	v_mul_f32_e32 v45, v45, v46
	v_cndmask_b32_e32 v45, v45, v44, vcc
	v_cmp_gt_u32_e32 vcc, s15, v47
	v_sub_f32_e32 v14, v14, v45
	s_nop 0
	v_cndmask_b32_e32 v14, 0, v14, vcc
	v_cmp_eq_f32_e32 vcc, 0, v50
	v_rcp_f32_e32 v50, v50
	v_mul_f32_e32 v49, 0x3f317218, v49
	s_nop 0
	v_mul_f32_e32 v50, v50, v48
	v_mul_f32_e32 v49, v49, v50
	v_cndmask_b32_e32 v49, v49, v48, vcc
	v_cmp_gt_u32_e32 vcc, s15, v51
	v_sub_f32_e32 v15, v15, v49
	s_nop 0
	v_cndmask_b32_e32 v15, 0, v15, vcc
	v_cmp_eq_f32_e32 vcc, 0, v54
	v_rcp_f32_e32 v54, v54
	v_mul_f32_e32 v53, 0x3f317218, v53
	s_nop 0
	v_mul_f32_e32 v54, v54, v52
	v_mul_f32_e32 v53, v53, v54
	v_cndmask_b32_e32 v53, v53, v52, vcc
	v_cmp_gt_u32_e32 vcc, s15, v55
	v_sub_f32_e32 v16, v16, v53
	s_nop 0
	v_cndmask_b32_e32 v16, 0, v16, vcc
	v_cmp_eq_f32_e32 vcc, 0, v58
	v_rcp_f32_e32 v58, v58
	v_mul_f32_e32 v57, 0x3f317218, v57
	s_nop 0
	v_mul_f32_e32 v58, v58, v56
	v_mul_f32_e32 v57, v57, v58
	v_cndmask_b32_e32 v57, v57, v56, vcc
	v_cmp_gt_u32_e32 vcc, s15, v59
	v_sub_f32_e32 v17, v17, v57
	s_nop 0
	v_cndmask_b32_e32 v17, 0, v17, vcc
	v_add_f32_e32 v18, v18, v60
	v_add_f32_e32 v19, v19, v60
	v_add_f32_e32 v20, v20, v60
	v_add_f32_e32 v21, v21, v60
	v_mul_f32_e64 v44, |v18|, s14
	v_mul_f32_e64 v48, |v19|, s14
	v_mul_f32_e64 v52, |v20|, s14
	v_mul_f32_e64 v56, |v21|, s14
	v_exp_f32_e32 v44, v44
	v_exp_f32_e32 v48, v48
	v_exp_f32_e32 v52, v52
	v_exp_f32_e32 v56, v56
	v_add_u32_e32 v47, 8, v65
	v_add_u32_e32 v51, 9, v65
	v_add_u32_e32 v55, 10, v65
	v_add_u32_e32 v59, 11, v65
	v_add_f32_e32 v45, 1.0, v44
	v_add_f32_e32 v49, 1.0, v48
	v_add_f32_e32 v53, 1.0, v52
	v_add_f32_e32 v57, 1.0, v56
	v_add_f32_e32 v46, -1.0, v45
	v_add_f32_e32 v50, -1.0, v49
	v_add_f32_e32 v54, -1.0, v53
	v_add_f32_e32 v58, -1.0, v57
	v_log_f32_e32 v45, v45
	v_log_f32_e32 v49, v49
	v_log_f32_e32 v53, v53
	v_log_f32_e32 v57, v57
	v_min_f32_e32 v18, 0, v18
	v_min_f32_e32 v19, 0, v19
	v_min_f32_e32 v20, 0, v20
	v_min_f32_e32 v21, 0, v21
	v_cmp_eq_f32_e32 vcc, 0, v46
	v_rcp_f32_e32 v46, v46
	v_mul_f32_e32 v45, 0x3f317218, v45
	s_nop 0
	v_mul_f32_e32 v46, v46, v44
	v_mul_f32_e32 v45, v45, v46
	v_cndmask_b32_e32 v45, v45, v44, vcc
	v_cmp_gt_u32_e32 vcc, s15, v47
	v_sub_f32_e32 v18, v18, v45
	s_nop 0
	v_cndmask_b32_e32 v18, 0, v18, vcc
	v_cmp_eq_f32_e32 vcc, 0, v50
	v_rcp_f32_e32 v50, v50
	v_mul_f32_e32 v49, 0x3f317218, v49
	s_nop 0
	v_mul_f32_e32 v50, v50, v48
	v_mul_f32_e32 v49, v49, v50
	v_cndmask_b32_e32 v49, v49, v48, vcc
	v_cmp_gt_u32_e32 vcc, s15, v51
	v_sub_f32_e32 v19, v19, v49
	s_nop 0
	v_cndmask_b32_e32 v19, 0, v19, vcc
	v_cmp_eq_f32_e32 vcc, 0, v54
	v_rcp_f32_e32 v54, v54
	v_mul_f32_e32 v53, 0x3f317218, v53
	s_nop 0
	v_mul_f32_e32 v54, v54, v52
	v_mul_f32_e32 v53, v53, v54
	v_cndmask_b32_e32 v53, v53, v52, vcc
	v_cmp_gt_u32_e32 vcc, s15, v55
	v_sub_f32_e32 v20, v20, v53
	s_nop 0
	v_cndmask_b32_e32 v20, 0, v20, vcc
	v_cmp_eq_f32_e32 vcc, 0, v58
	v_rcp_f32_e32 v58, v58
	v_mul_f32_e32 v57, 0x3f317218, v57
	s_nop 0
	v_mul_f32_e32 v58, v58, v56
	v_mul_f32_e32 v57, v57, v58
	v_cndmask_b32_e32 v57, v57, v56, vcc
	v_cmp_gt_u32_e32 vcc, s15, v59
	v_sub_f32_e32 v21, v21, v57
	s_nop 0
	v_cndmask_b32_e32 v21, 0, v21, vcc
	v_add_f32_e32 v22, v22, v60
	v_add_f32_e32 v23, v23, v60
	v_add_f32_e32 v24, v24, v60
	v_add_f32_e32 v25, v25, v60
	v_mul_f32_e64 v44, |v22|, s14
	v_mul_f32_e64 v48, |v23|, s14
	v_mul_f32_e64 v52, |v24|, s14
	v_mul_f32_e64 v56, |v25|, s14
	v_exp_f32_e32 v44, v44
	v_exp_f32_e32 v48, v48
	v_exp_f32_e32 v52, v52
	v_exp_f32_e32 v56, v56
	v_add_u32_e32 v47, 12, v65
	v_add_u32_e32 v51, 13, v65
	v_add_u32_e32 v55, 14, v65
	v_add_u32_e32 v59, 15, v65
	v_add_f32_e32 v45, 1.0, v44
	v_add_f32_e32 v49, 1.0, v48
	v_add_f32_e32 v53, 1.0, v52
	v_add_f32_e32 v57, 1.0, v56
	v_add_f32_e32 v46, -1.0, v45
	v_add_f32_e32 v50, -1.0, v49
	v_add_f32_e32 v54, -1.0, v53
	v_add_f32_e32 v58, -1.0, v57
	v_log_f32_e32 v45, v45
	v_log_f32_e32 v49, v49
	v_log_f32_e32 v53, v53
	v_log_f32_e32 v57, v57
	v_min_f32_e32 v22, 0, v22
	v_min_f32_e32 v23, 0, v23
	v_min_f32_e32 v24, 0, v24
	v_min_f32_e32 v25, 0, v25
	v_cmp_eq_f32_e32 vcc, 0, v46
	v_rcp_f32_e32 v46, v46
	v_mul_f32_e32 v45, 0x3f317218, v45
	s_nop 0
	v_mul_f32_e32 v46, v46, v44
	v_mul_f32_e32 v45, v45, v46
	v_cndmask_b32_e32 v45, v45, v44, vcc
	v_cmp_gt_u32_e32 vcc, s15, v47
	v_sub_f32_e32 v22, v22, v45
	s_nop 0
	v_cndmask_b32_e32 v22, 0, v22, vcc
	v_cmp_eq_f32_e32 vcc, 0, v50
	v_rcp_f32_e32 v50, v50
	v_mul_f32_e32 v49, 0x3f317218, v49
	s_nop 0
	v_mul_f32_e32 v50, v50, v48
	v_mul_f32_e32 v49, v49, v50
	v_cndmask_b32_e32 v49, v49, v48, vcc
	v_cmp_gt_u32_e32 vcc, s15, v51
	v_sub_f32_e32 v23, v23, v49
	s_nop 0
	v_cndmask_b32_e32 v23, 0, v23, vcc
	v_cmp_eq_f32_e32 vcc, 0, v54
	v_rcp_f32_e32 v54, v54
	v_mul_f32_e32 v53, 0x3f317218, v53
	s_nop 0
	v_mul_f32_e32 v54, v54, v52
	v_mul_f32_e32 v53, v53, v54
	v_cndmask_b32_e32 v53, v53, v52, vcc
	v_cmp_gt_u32_e32 vcc, s15, v55
	v_sub_f32_e32 v24, v24, v53
	s_nop 0
	v_cndmask_b32_e32 v24, 0, v24, vcc
	v_cmp_eq_f32_e32 vcc, 0, v58
	v_rcp_f32_e32 v58, v58
	v_mul_f32_e32 v57, 0x3f317218, v57
	s_nop 0
	v_mul_f32_e32 v58, v58, v56
	v_mul_f32_e32 v57, v57, v58
	v_cndmask_b32_e32 v57, v57, v56, vcc
	v_cmp_gt_u32_e32 vcc, s15, v59
	v_sub_f32_e32 v25, v25, v57
	s_nop 0
	v_cndmask_b32_e32 v25, 0, v25, vcc
	v_add_f32_e32 v26, v26, v60
	v_add_f32_e32 v27, v27, v60
; __device__ __forceinline__ float logsigf_(float x) { return fminf(x, 0.f) - log1pf(__expf(-fabsf(x))); }
; __device__ __forceinline__ void hyb_prep_phase(const Params& p, float* sm, int bid, int nb) {
;     ...
;     for (int i = 0; i < 33; i++) {
;       const int pr = p0 + i;
;       float lf = 0.f;
;       if (pr >= PADR && pr < LP) lf = logsigf_(zg[((size_t)b * LP + pr) * 16 + h] + bf);
;       x[i] = lf; s += lf;
;     }
	v_add_f32_e32 v28, v28, v60
	v_add_f32_e32 v29, v29, v60
	v_mul_f32_e64 v44, |v26|, s14
	v_mul_f32_e64 v48, |v27|, s14
	v_mul_f32_e64 v52, |v28|, s14
	v_mul_f32_e64 v56, |v29|, s14
	v_exp_f32_e32 v44, v44
	v_exp_f32_e32 v48, v48
	v_exp_f32_e32 v52, v52
	v_exp_f32_e32 v56, v56
	v_add_u32_e32 v47, 16, v65
	v_add_u32_e32 v51, 17, v65
	v_add_u32_e32 v55, 18, v65
	v_add_u32_e32 v59, 19, v65
	v_add_f32_e32 v45, 1.0, v44
	v_add_f32_e32 v49, 1.0, v48
	v_add_f32_e32 v53, 1.0, v52
	v_add_f32_e32 v57, 1.0, v56
	v_add_f32_e32 v46, -1.0, v45
	v_add_f32_e32 v50, -1.0, v49
	v_add_f32_e32 v54, -1.0, v53
	v_add_f32_e32 v58, -1.0, v57
	v_log_f32_e32 v45, v45
	v_log_f32_e32 v49, v49
	v_log_f32_e32 v53, v53
	v_log_f32_e32 v57, v57
	v_min_f32_e32 v26, 0, v26
	v_min_f32_e32 v27, 0, v27
	v_min_f32_e32 v28, 0, v28
	v_min_f32_e32 v29, 0, v29
	v_cmp_eq_f32_e32 vcc, 0, v46
	v_rcp_f32_e32 v46, v46
	v_mul_f32_e32 v45, 0x3f317218, v45
	s_nop 0
	v_mul_f32_e32 v46, v46, v44
	v_mul_f32_e32 v45, v45, v46
	v_cndmask_b32_e32 v45, v45, v44, vcc
	v_cmp_gt_u32_e32 vcc, s15, v47
	v_sub_f32_e32 v26, v26, v45
	s_nop 0
	v_cndmask_b32_e32 v26, 0, v26, vcc
	v_cmp_eq_f32_e32 vcc, 0, v50
	v_rcp_f32_e32 v50, v50
	v_mul_f32_e32 v49, 0x3f317218, v49
	s_nop 0
	v_mul_f32_e32 v50, v50, v48
	v_mul_f32_e32 v49, v49, v50
	v_cndmask_b32_e32 v49, v49, v48, vcc
	v_cmp_gt_u32_e32 vcc, s15, v51
	v_sub_f32_e32 v27, v27, v49
	s_nop 0
	v_cndmask_b32_e32 v27, 0, v27, vcc
	v_cmp_eq_f32_e32 vcc, 0, v54
	v_rcp_f32_e32 v54, v54
	v_mul_f32_e32 v53, 0x3f317218, v53
	s_nop 0
	v_mul_f32_e32 v54, v54, v52
	v_mul_f32_e32 v53, v53, v54
	v_cndmask_b32_e32 v53, v53, v52, vcc
	v_cmp_gt_u32_e32 vcc, s15, v55
	v_sub_f32_e32 v28, v28, v53
	s_nop 0
	v_cndmask_b32_e32 v28, 0, v28, vcc
	v_cmp_eq_f32_e32 vcc, 0, v58
	v_rcp_f32_e32 v58, v58
	v_mul_f32_e32 v57, 0x3f317218, v57
	s_nop 0
	v_mul_f32_e32 v58, v58, v56
	v_mul_f32_e32 v57, v57, v58
	v_cndmask_b32_e32 v57, v57, v56, vcc
	v_cmp_gt_u32_e32 vcc, s15, v59
	v_sub_f32_e32 v29, v29, v57
	s_nop 0
	v_cndmask_b32_e32 v29, 0, v29, vcc
	v_add_f32_e32 v30, v30, v60
	v_add_f32_e32 v31, v31, v60
	v_add_f32_e32 v32, v32, v60
	v_add_f32_e32 v33, v33, v60
	v_mul_f32_e64 v44, |v30|, s14
	v_mul_f32_e64 v48, |v31|, s14
	v_mul_f32_e64 v52, |v32|, s14
	v_mul_f32_e64 v56, |v33|, s14
	v_exp_f32_e32 v44, v44
	v_exp_f32_e32 v48, v48
	v_exp_f32_e32 v52, v52
	v_exp_f32_e32 v56, v56
	v_add_u32_e32 v47, 20, v65
	v_add_u32_e32 v51, 21, v65
	v_add_u32_e32 v55, 22, v65
	v_add_u32_e32 v59, 23, v65
	v_add_f32_e32 v45, 1.0, v44
	v_add_f32_e32 v49, 1.0, v48
	v_add_f32_e32 v53, 1.0, v52
	v_add_f32_e32 v57, 1.0, v56
	v_add_f32_e32 v46, -1.0, v45
	v_add_f32_e32 v50, -1.0, v49
	v_add_f32_e32 v54, -1.0, v53
	v_add_f32_e32 v58, -1.0, v57
	v_log_f32_e32 v45, v45
	v_log_f32_e32 v49, v49
	v_log_f32_e32 v53, v53
	v_log_f32_e32 v57, v57
	v_min_f32_e32 v30, 0, v30
	v_min_f32_e32 v31, 0, v31
	v_min_f32_e32 v32, 0, v32
	v_min_f32_e32 v33, 0, v33
	v_cmp_eq_f32_e32 vcc, 0, v46
	v_rcp_f32_e32 v46, v46
	v_mul_f32_e32 v45, 0x3f317218, v45
	s_nop 0
	v_mul_f32_e32 v46, v46, v44
	v_mul_f32_e32 v45, v45, v46
	v_cndmask_b32_e32 v45, v45, v44, vcc
	v_cmp_gt_u32_e32 vcc, s15, v47
	v_sub_f32_e32 v30, v30, v45
	s_nop 0
	v_cndmask_b32_e32 v30, 0, v30, vcc
	v_cmp_eq_f32_e32 vcc, 0, v50
	v_rcp_f32_e32 v50, v50
	v_mul_f32_e32 v49, 0x3f317218, v49
	s_nop 0
	v_mul_f32_e32 v50, v50, v48
	v_mul_f32_e32 v49, v49, v50
	v_cndmask_b32_e32 v49, v49, v48, vcc
	v_cmp_gt_u32_e32 vcc, s15, v51
	v_sub_f32_e32 v31, v31, v49
	s_nop 0
	v_cndmask_b32_e32 v31, 0, v31, vcc
	v_cmp_eq_f32_e32 vcc, 0, v54
	v_rcp_f32_e32 v54, v54
	v_mul_f32_e32 v53, 0x3f317218, v53
	s_nop 0
	v_mul_f32_e32 v54, v54, v52
	v_mul_f32_e32 v53, v53, v54
	v_cndmask_b32_e32 v53, v53, v52, vcc
	v_cmp_gt_u32_e32 vcc, s15, v55
	v_sub_f32_e32 v32, v32, v53
	s_nop 0
	v_cndmask_b32_e32 v32, 0, v32, vcc
	v_cmp_eq_f32_e32 vcc, 0, v58
	v_rcp_f32_e32 v58, v58
	v_mul_f32_e32 v57, 0x3f317218, v57
	s_nop 0
	v_mul_f32_e32 v58, v58, v56
	v_mul_f32_e32 v57, v57, v58
	v_cndmask_b32_e32 v57, v57, v56, vcc
	v_cmp_gt_u32_e32 vcc, s15, v59
	v_sub_f32_e32 v33, v33, v57
	s_nop 0
	v_cndmask_b32_e32 v33, 0, v33, vcc
	v_add_f32_e32 v34, v34, v60
	v_add_f32_e32 v35, v35, v60
	v_add_f32_e32 v36, v36, v60
	v_add_f32_e32 v37, v37, v60
	v_mul_f32_e64 v44, |v34|, s14
	v_mul_f32_e64 v48, |v35|, s14
	v_mul_f32_e64 v52, |v36|, s14
	v_mul_f32_e64 v56, |v37|, s14
	v_exp_f32_e32 v44, v44
	v_exp_f32_e32 v48, v48
	v_exp_f32_e32 v52, v52
	v_exp_f32_e32 v56, v56
	v_add_u32_e32 v47, 24, v65
	v_add_u32_e32 v51, 25, v65
	v_add_u32_e32 v55, 26, v65
	v_add_u32_e32 v59, 27, v65
	v_add_f32_e32 v45, 1.0, v44
	v_add_f32_e32 v49, 1.0, v48
	v_add_f32_e32 v53, 1.0, v52
	v_add_f32_e32 v57, 1.0, v56
	v_add_f32_e32 v46, -1.0, v45
	v_add_f32_e32 v50, -1.0, v49
	v_add_f32_e32 v54, -1.0, v53
	v_add_f32_e32 v58, -1.0, v57
	v_log_f32_e32 v45, v45
	v_log_f32_e32 v49, v49
	v_log_f32_e32 v53, v53
	v_log_f32_e32 v57, v57
	v_min_f32_e32 v34, 0, v34
	v_min_f32_e32 v35, 0, v35
	v_min_f32_e32 v36, 0, v36
	v_min_f32_e32 v37, 0, v37
	v_cmp_eq_f32_e32 vcc, 0, v46
	v_rcp_f32_e32 v46, v46
	v_mul_f32_e32 v45, 0x3f317218, v45
	s_nop 0
	v_mul_f32_e32 v46, v46, v44
	v_mul_f32_e32 v45, v45, v46
	v_cndmask_b32_e32 v45, v45, v44, vcc
	v_cmp_gt_u32_e32 vcc, s15, v47
	v_sub_f32_e32 v34, v34, v45
	s_nop 0
	v_cndmask_b32_e32 v34, 0, v34, vcc
	v_cmp_eq_f32_e32 vcc, 0, v50
	v_rcp_f32_e32 v50, v50
	v_mul_f32_e32 v49, 0x3f317218, v49
	s_nop 0
	v_mul_f32_e32 v50, v50, v48
	v_mul_f32_e32 v49, v49, v50
	v_cndmask_b32_e32 v49, v49, v48, vcc
	v_cmp_gt_u32_e32 vcc, s15, v51
	v_sub_f32_e32 v35, v35, v49
	s_nop 0
	v_cndmask_b32_e32 v35, 0, v35, vcc
	v_cmp_eq_f32_e32 vcc, 0, v54
; __device__ __forceinline__ float logsigf_(float x) { return fminf(x, 0.f) - log1pf(__expf(-fabsf(x))); }
; __device__ __forceinline__ void hyb_prep_phase(const Params& p, float* sm, int bid, int nb) {
;     ...
;     for (int i = 0; i < 33; i++) {
;       const int pr = p0 + i;
;       float lf = 0.f;
;       if (pr >= PADR && pr < LP) lf = logsigf_(zg[((size_t)b * LP + pr) * 16 + h] + bf);
;       x[i] = lf; s += lf;
;     }
;     float inc = s;
; #pragma unroll
;     for (int o = 1; o < 64; o <<= 1) {
;       const float t = __shfl_up(inc, o);
;       if (lane >= o) inc += t;
;     }
;     __syncthreads();
;     if (lane == 63) sm[wave] = inc;
;     __syncthreads();
;     float run = inc - s;
;     if (wave > 0) run += sm[0];
;     if (wave > 1) run += sm[1];
;     if (wave > 2) run += sm[2];
; #pragma unroll
;     for (int i = 0; i < 33; i++) {
;       const int pr = p0 + i;
;       run += x[i];
	v_rcp_f32_e32 v54, v54
	v_mul_f32_e32 v53, 0x3f317218, v53
	s_nop 0
	v_mul_f32_e32 v54, v54, v52
	v_mul_f32_e32 v53, v53, v54
	v_cndmask_b32_e32 v53, v53, v52, vcc
	v_cmp_gt_u32_e32 vcc, s15, v55
	v_sub_f32_e32 v36, v36, v53
	s_nop 0
	v_cndmask_b32_e32 v36, 0, v36, vcc
	v_cmp_eq_f32_e32 vcc, 0, v58
	v_rcp_f32_e32 v58, v58
	v_mul_f32_e32 v57, 0x3f317218, v57
	s_nop 0
	v_mul_f32_e32 v58, v58, v56
	v_mul_f32_e32 v57, v57, v58
	v_cndmask_b32_e32 v57, v57, v56, vcc
	v_cmp_gt_u32_e32 vcc, s15, v59
	v_sub_f32_e32 v37, v37, v57
	s_nop 0
	v_cndmask_b32_e32 v37, 0, v37, vcc
	v_add_f32_e32 v38, v38, v60
	v_add_f32_e32 v39, v39, v60
	v_add_f32_e32 v40, v40, v60
	v_add_f32_e32 v41, v41, v60
	v_mul_f32_e64 v44, |v38|, s14
	v_mul_f32_e64 v48, |v39|, s14
	v_mul_f32_e64 v52, |v40|, s14
	v_mul_f32_e64 v56, |v41|, s14
	v_exp_f32_e32 v44, v44
	v_exp_f32_e32 v48, v48
	v_exp_f32_e32 v52, v52
	v_exp_f32_e32 v56, v56
	v_add_u32_e32 v47, 28, v65
	v_add_u32_e32 v51, 29, v65
	v_add_u32_e32 v55, 30, v65
	v_add_u32_e32 v59, 31, v65
	v_add_f32_e32 v45, 1.0, v44
	v_add_f32_e32 v49, 1.0, v48
	v_add_f32_e32 v53, 1.0, v52
	v_add_f32_e32 v57, 1.0, v56
	v_add_f32_e32 v46, -1.0, v45
	v_add_f32_e32 v50, -1.0, v49
	v_add_f32_e32 v54, -1.0, v53
	v_add_f32_e32 v58, -1.0, v57
	v_log_f32_e32 v45, v45
	v_log_f32_e32 v49, v49
	v_log_f32_e32 v53, v53
	v_log_f32_e32 v57, v57
	v_min_f32_e32 v38, 0, v38
	v_min_f32_e32 v39, 0, v39
	v_min_f32_e32 v40, 0, v40
	v_min_f32_e32 v41, 0, v41
	v_cmp_eq_f32_e32 vcc, 0, v46
	v_rcp_f32_e32 v46, v46
	v_mul_f32_e32 v45, 0x3f317218, v45
	s_nop 0
	v_mul_f32_e32 v46, v46, v44
	v_mul_f32_e32 v45, v45, v46
	v_cndmask_b32_e32 v45, v45, v44, vcc
	v_cmp_gt_u32_e32 vcc, s15, v47
	v_sub_f32_e32 v38, v38, v45
	s_nop 0
	v_cndmask_b32_e32 v38, 0, v38, vcc
	v_cmp_eq_f32_e32 vcc, 0, v50
	v_rcp_f32_e32 v50, v50
	v_mul_f32_e32 v49, 0x3f317218, v49
	s_nop 0
	v_mul_f32_e32 v50, v50, v48
	v_mul_f32_e32 v49, v49, v50
	v_cndmask_b32_e32 v49, v49, v48, vcc
	v_cmp_gt_u32_e32 vcc, s15, v51
	v_sub_f32_e32 v39, v39, v49
	s_nop 0
	v_cndmask_b32_e32 v39, 0, v39, vcc
	v_cmp_eq_f32_e32 vcc, 0, v54
	v_rcp_f32_e32 v54, v54
	v_mul_f32_e32 v53, 0x3f317218, v53
	s_nop 0
	v_mul_f32_e32 v54, v54, v52
	v_mul_f32_e32 v53, v53, v54
	v_cndmask_b32_e32 v53, v53, v52, vcc
	v_cmp_gt_u32_e32 vcc, s15, v55
	v_sub_f32_e32 v40, v40, v53
	s_nop 0
	v_cndmask_b32_e32 v40, 0, v40, vcc
	v_cmp_eq_f32_e32 vcc, 0, v58
	v_rcp_f32_e32 v58, v58
	v_mul_f32_e32 v57, 0x3f317218, v57
	s_nop 0
	v_mul_f32_e32 v58, v58, v56
	v_mul_f32_e32 v57, v57, v58
	v_cndmask_b32_e32 v57, v57, v56, vcc
	v_cmp_gt_u32_e32 vcc, s15, v59
	v_sub_f32_e32 v41, v41, v57
	s_nop 0
	v_cndmask_b32_e32 v41, 0, v41, vcc
	v_add_f32_e32 v42, v42, v60
	v_mul_f32_e64 v44, |v42|, s14
	v_exp_f32_e32 v44, v44
	v_add_u32_e32 v47, 32, v65
	v_add_f32_e32 v45, 1.0, v44
	v_add_f32_e32 v46, -1.0, v45
	v_log_f32_e32 v45, v45
	v_min_f32_e32 v42, 0, v42
	v_cmp_eq_f32_e32 vcc, 0, v46
	v_rcp_f32_e32 v46, v46
	v_mul_f32_e32 v45, 0x3f317218, v45
	s_nop 0
	v_mul_f32_e32 v46, v46, v44
	v_mul_f32_e32 v45, v45, v46
	v_cndmask_b32_e32 v45, v45, v44, vcc
	v_cmp_gt_u32_e32 vcc, s15, v47
	v_sub_f32_e32 v42, v42, v45
	s_nop 0
	v_cndmask_b32_e32 v42, 0, v42, vcc
	v_add_f32_e32 v67, v10, v11
	v_add_f32_e32 v67, v67, v12
	v_add_f32_e32 v67, v67, v13
	v_add_f32_e32 v67, v67, v14
	v_add_f32_e32 v67, v67, v15
	v_add_f32_e32 v67, v67, v16
	v_add_f32_e32 v67, v67, v17
	v_add_f32_e32 v67, v67, v18
	v_add_f32_e32 v67, v67, v19
	v_add_f32_e32 v67, v67, v20
	v_add_f32_e32 v67, v67, v21
	v_add_f32_e32 v67, v67, v22
	v_add_f32_e32 v67, v67, v23
	v_add_f32_e32 v67, v67, v24
	v_add_f32_e32 v67, v67, v25
	v_add_f32_e32 v67, v67, v26
	v_add_f32_e32 v67, v67, v27
	v_add_f32_e32 v67, v67, v28
	v_add_f32_e32 v67, v67, v29
	v_add_f32_e32 v67, v67, v30
	v_add_f32_e32 v67, v67, v31
	v_add_f32_e32 v67, v67, v32
	v_add_f32_e32 v67, v67, v33
	v_add_f32_e32 v67, v67, v34
	v_add_f32_e32 v67, v67, v35
	v_add_f32_e32 v67, v67, v36
	v_add_f32_e32 v67, v67, v37
	v_add_f32_e32 v67, v67, v38
	v_add_f32_e32 v67, v67, v39
	v_add_f32_e32 v67, v67, v40
	v_add_f32_e32 v67, v67, v41
	v_add_f32_e32 v67, v67, v42
	v_mov_b32_e32 v68, v67
	s_nop 1
	v_add_f32_dpp v68, v68, v68 row_shr:1 row_mask:0xf bank_mask:0xf bound_ctrl:1
	s_nop 1
	v_add_f32_dpp v68, v68, v68 row_shr:2 row_mask:0xf bank_mask:0xf bound_ctrl:1
	s_nop 1
	v_add_f32_dpp v68, v68, v68 row_shr:4 row_mask:0xf bank_mask:0xf bound_ctrl:1
	s_nop 1
	v_add_f32_dpp v68, v68, v68 row_shr:8 row_mask:0xf bank_mask:0xf bound_ctrl:1
	s_nop 1
	v_add_f32_dpp v68, v68, v68 row_bcast:15 row_mask:0xa bank_mask:0xf
	s_nop 1
	v_add_f32_dpp v68, v68, v68 row_bcast:31 row_mask:0xc bank_mask:0xf
	s_nop 1
	v_readlane_b32 s16, v68, 63
	v_lshlrev_b32_e32 v71, 2, v79
	v_readfirstlane_b32 s17, v79
	v_mov_b32_e32 v70, s16
	ds_write_b32 v71, v70
	s_waitcnt lgkmcnt(0)
	s_barrier
	v_mov_b32_e32 v71, 0
	ds_read_b128 v[70:73], v71
	v_sub_f32_e32 v69, v68, v67
	s_waitcnt lgkmcnt(0)
	s_cmp_gt_u32 s17, 0
	s_cselect_b32 s18, -1, 0
	v_and_b32_e32 v70, s18, v70
	v_add_f32_e32 v69, v69, v70
	s_cmp_gt_u32 s17, 1
	s_cselect_b32 s18, -1, 0
	v_and_b32_e32 v71, s18, v71
	v_add_f32_e32 v69, v69, v71
	s_cmp_gt_u32 s17, 2
	s_cselect_b32 s18, -1, 0
	v_and_b32_e32 v72, s18, v72
	v_add_f32_e32 v69, v69, v72
	v_add_f32_e32 v10, v69, v10
	v_add_f32_e32 v11, v10, v11
	v_add_f32_e32 v12, v11, v12
	v_add_f32_e32 v13, v12, v13
	v_add_f32_e32 v14, v13, v14
	v_add_f32_e32 v15, v14, v15
	v_add_f32_e32 v16, v15, v16
	v_add_f32_e32 v17, v16, v17
	v_add_f32_e32 v18, v17, v18
	v_add_f32_e32 v19, v18, v19
	v_add_f32_e32 v20, v19, v20
	v_add_f32_e32 v21, v20, v21
	v_add_f32_e32 v22, v21, v22
	v_add_f32_e32 v23, v22, v23
	v_add_f32_e32 v24, v23, v24
	v_add_f32_e32 v25, v24, v25
	v_add_f32_e32 v26, v25, v26
	v_add_f32_e32 v27, v26, v27
	v_add_f32_e32 v28, v27, v28
	v_add_f32_e32 v29, v28, v29
	v_add_f32_e32 v30, v29, v30
	v_add_f32_e32 v31, v30, v31
	v_add_f32_e32 v32, v31, v32
	v_add_f32_e32 v33, v32, v33
	v_add_f32_e32 v34, v33, v34
	v_add_f32_e32 v35, v34, v35
	v_add_f32_e32 v36, v35, v36
	v_add_f32_e32 v37, v36, v37
	v_add_f32_e32 v38, v37, v38
	v_add_f32_e32 v39, v38, v39
	v_add_f32_e32 v40, v39, v40
	v_add_f32_e32 v41, v40, v41
	v_add_f32_e32 v42, v41, v42
	s_cmp_lt_u32 s17, 3
	s_cbranch_scc0 .Lcs_masked
; __device__ __forceinline__ void hyb_prep_phase(const Params& p, float* sm, int bid, int nb) {
;     ...
; #pragma unroll
;     for (int i = 0; i < 33; i++) {
;       const int pr = p0 + i;
;       run += x[i];
;       if (pr < LP) cf[((size_t)b * 8 + h) * LP + pr] = run;
;     }
;   }
;   {
;     unsigned* stats = (unsigned*)(p.ws + OFF_STAT);
;     for (int it = bid * 4 + wave; it < NB * 8 * 65; it += nb * 4) {
;       const int bh = it / 65, seg = it - bh * 65;
;       const int b = bh >> 3, h = bh & 7;
;       float mq = 0.f, mk = 0.f;
; #pragma unroll 4
;       for (int g8 = 0; g8 < 16; g8++) {
;         const size_t row = (size_t)b * LP + seg * 128 + g8 * 8 + (lane >> 3);
;         const uint4 uq = *(const uint4*)(z + row * ZLD + h * 64 + (lane & 7) * 8);
	global_store_dword v64, v10, s[10:11]
	global_store_dword v64, v11, s[10:11] offset:4
	global_store_dword v64, v12, s[10:11] offset:8
	global_store_dword v64, v13, s[10:11] offset:12
	global_store_dword v64, v14, s[10:11] offset:16
	global_store_dword v64, v15, s[10:11] offset:20
	global_store_dword v64, v16, s[10:11] offset:24
	global_store_dword v64, v17, s[10:11] offset:28
	global_store_dword v64, v18, s[10:11] offset:32
	global_store_dword v64, v19, s[10:11] offset:36
	global_store_dword v64, v20, s[10:11] offset:40
	global_store_dword v64, v21, s[10:11] offset:44
	global_store_dword v64, v22, s[10:11] offset:48
	global_store_dword v64, v23, s[10:11] offset:52
	global_store_dword v64, v24, s[10:11] offset:56
	global_store_dword v64, v25, s[10:11] offset:60
	global_store_dword v64, v26, s[10:11] offset:64
	global_store_dword v64, v27, s[10:11] offset:68
	global_store_dword v64, v28, s[10:11] offset:72
	global_store_dword v64, v29, s[10:11] offset:76
	global_store_dword v64, v30, s[10:11] offset:80
	global_store_dword v64, v31, s[10:11] offset:84
	global_store_dword v64, v32, s[10:11] offset:88
	global_store_dword v64, v33, s[10:11] offset:92
	global_store_dword v64, v34, s[10:11] offset:96
	global_store_dword v64, v35, s[10:11] offset:100
	global_store_dword v64, v36, s[10:11] offset:104
	global_store_dword v64, v37, s[10:11] offset:108
	global_store_dword v64, v38, s[10:11] offset:112
	global_store_dword v64, v39, s[10:11] offset:116
	global_store_dword v64, v40, s[10:11] offset:120
	global_store_dword v64, v41, s[10:11] offset:124
	global_store_dword v64, v42, s[10:11] offset:128
	s_branch .Lcs_done
.Lcs_masked:
	v_cmp_lt_i32_e32 vcc, 0, v66
	s_nop 1
	s_mov_b64 exec, vcc
	global_store_dword v64, v10, s[10:11]
	v_cmp_lt_i32_e32 vcc, 1, v66
	s_nop 1
	s_mov_b64 exec, vcc
	global_store_dword v64, v11, s[10:11] offset:4
	v_cmp_lt_i32_e32 vcc, 2, v66
	s_nop 1
	s_mov_b64 exec, vcc
	global_store_dword v64, v12, s[10:11] offset:8
	v_cmp_lt_i32_e32 vcc, 3, v66
	s_nop 1
	s_mov_b64 exec, vcc
	global_store_dword v64, v13, s[10:11] offset:12
	v_cmp_lt_i32_e32 vcc, 4, v66
	s_nop 1
	s_mov_b64 exec, vcc
	global_store_dword v64, v14, s[10:11] offset:16
	v_cmp_lt_i32_e32 vcc, 5, v66
	s_nop 1
	s_mov_b64 exec, vcc
	global_store_dword v64, v15, s[10:11] offset:20
	v_cmp_lt_i32_e32 vcc, 6, v66
	s_nop 1
	s_mov_b64 exec, vcc
	global_store_dword v64, v16, s[10:11] offset:24
	v_cmp_lt_i32_e32 vcc, 7, v66
	s_nop 1
	s_mov_b64 exec, vcc
	global_store_dword v64, v17, s[10:11] offset:28
	v_cmp_lt_i32_e32 vcc, 8, v66
	s_nop 1
	s_mov_b64 exec, vcc
	global_store_dword v64, v18, s[10:11] offset:32
	v_cmp_lt_i32_e32 vcc, 9, v66
	s_nop 1
	s_mov_b64 exec, vcc
	global_store_dword v64, v19, s[10:11] offset:36
	v_cmp_lt_i32_e32 vcc, 10, v66
	s_nop 1
	s_mov_b64 exec, vcc
	global_store_dword v64, v20, s[10:11] offset:40
	v_cmp_lt_i32_e32 vcc, 11, v66
	s_nop 1
	s_mov_b64 exec, vcc
	global_store_dword v64, v21, s[10:11] offset:44
	v_cmp_lt_i32_e32 vcc, 12, v66
	s_nop 1
	s_mov_b64 exec, vcc
	global_store_dword v64, v22, s[10:11] offset:48
	v_cmp_lt_i32_e32 vcc, 13, v66
	s_nop 1
	s_mov_b64 exec, vcc
	global_store_dword v64, v23, s[10:11] offset:52
	v_cmp_lt_i32_e32 vcc, 14, v66
	s_nop 1
	s_mov_b64 exec, vcc
	global_store_dword v64, v24, s[10:11] offset:56
	v_cmp_lt_i32_e32 vcc, 15, v66
	s_nop 1
	s_mov_b64 exec, vcc
	global_store_dword v64, v25, s[10:11] offset:60
	v_cmp_lt_i32_e32 vcc, 16, v66
	s_nop 1
	s_mov_b64 exec, vcc
	global_store_dword v64, v26, s[10:11] offset:64
	v_cmp_lt_i32_e32 vcc, 17, v66
	s_nop 1
	s_mov_b64 exec, vcc
	global_store_dword v64, v27, s[10:11] offset:68
	v_cmp_lt_i32_e32 vcc, 18, v66
	s_nop 1
	s_mov_b64 exec, vcc
	global_store_dword v64, v28, s[10:11] offset:72
	v_cmp_lt_i32_e32 vcc, 19, v66
	s_nop 1
	s_mov_b64 exec, vcc
	global_store_dword v64, v29, s[10:11] offset:76
	v_cmp_lt_i32_e32 vcc, 20, v66
	s_nop 1
	s_mov_b64 exec, vcc
	global_store_dword v64, v30, s[10:11] offset:80
	v_cmp_lt_i32_e32 vcc, 21, v66
	s_nop 1
	s_mov_b64 exec, vcc
	global_store_dword v64, v31, s[10:11] offset:84
	v_cmp_lt_i32_e32 vcc, 22, v66
	s_nop 1
	s_mov_b64 exec, vcc
	global_store_dword v64, v32, s[10:11] offset:88
	v_cmp_lt_i32_e32 vcc, 23, v66
	s_nop 1
	s_mov_b64 exec, vcc
	global_store_dword v64, v33, s[10:11] offset:92
	v_cmp_lt_i32_e32 vcc, 24, v66
	s_nop 1
	s_mov_b64 exec, vcc
	global_store_dword v64, v34, s[10:11] offset:96
	v_cmp_lt_i32_e32 vcc, 25, v66
	s_nop 1
	s_mov_b64 exec, vcc
	global_store_dword v64, v35, s[10:11] offset:100
	v_cmp_lt_i32_e32 vcc, 26, v66
	s_nop 1
	s_mov_b64 exec, vcc
	global_store_dword v64, v36, s[10:11] offset:104
	v_cmp_lt_i32_e32 vcc, 27, v66
	s_nop 1
	s_mov_b64 exec, vcc
	global_store_dword v64, v37, s[10:11] offset:108
	v_cmp_lt_i32_e32 vcc, 28, v66
	s_nop 1
	s_mov_b64 exec, vcc
	global_store_dword v64, v38, s[10:11] offset:112
	v_cmp_lt_i32_e32 vcc, 29, v66
	s_nop 1
	s_mov_b64 exec, vcc
	global_store_dword v64, v39, s[10:11] offset:116
	v_cmp_lt_i32_e32 vcc, 30, v66
	s_nop 1
	s_mov_b64 exec, vcc
	global_store_dword v64, v40, s[10:11] offset:120
	v_cmp_lt_i32_e32 vcc, 31, v66
	s_nop 1
	s_mov_b64 exec, vcc
	global_store_dword v64, v41, s[10:11] offset:124
	v_cmp_lt_i32_e32 vcc, 32, v66
	s_nop 1
	s_mov_b64 exec, vcc
	global_store_dword v64, v42, s[10:11] offset:128
	s_mov_b64 exec, -1
.Lcs_done:
.LBB0_2165:
	v_readlane_b32 s0, v244, 27
	s_waitcnt vmcnt(0)
	s_nop 0
	v_lshl_add_u32 v10, s0, 2, v79
	s_movk_i32 s0, 0x820
	v_cmp_gt_i32_e32 vcc, s0, v10
	s_and_saveexec_b64 s[0:1], vcc
	s_mov_b32 s28, s54
	s_cbranch_execz .LBB0_2172
	v_and_b32_e32 v8, 64, v215
	v_add_u32_e32 v8, 64, v8
	v_xor_b32_e32 v11, 32, v215
	v_cmp_lt_i32_e32 vcc, v11, v8
	v_xor_b32_e32 v13, 16, v215
	v_xor_b32_e32 v14, 8, v215
	v_cndmask_b32_e32 v11, v215, v11, vcc
	v_cmp_lt_i32_e32 vcc, v13, v8
	v_readlane_b32 s8, v247, 1
	v_readlane_b32 s10, v247, 3
	v_cndmask_b32_e32 v13, v215, v13, vcc
	v_cmp_lt_i32_e32 vcc, v14, v8
	v_readlane_b32 s11, v247, 4
	v_readlane_b32 s9, v247, 2
	v_cndmask_b32_e32 v14, v215, v14, vcc
	v_lshlrev_b32_e32 v20, 2, v14
	v_xor_b32_e32 v14, 4, v215
	v_cmp_lt_i32_e32 vcc, v14, v8
	v_readlane_b32 s4, v244, 27
	s_waitcnt lgkmcnt(0)
	v_lshrrev_b32_e32 v12, 3, v78
	v_cndmask_b32_e32 v14, v215, v14, vcc
	v_lshlrev_b32_e32 v21, 2, v14
	v_xor_b32_e32 v14, 2, v215
	v_cmp_lt_i32_e32 vcc, v14, v8
	v_cmp_eq_u32_e64 s[6:7], 0, v78
	s_lshl_b32 s2, s39, 2
	v_cndmask_b32_e32 v14, v215, v14, vcc
	v_lshlrev_b32_e32 v22, 2, v14
	v_xor_b32_e32 v14, 1, v215
	v_cmp_lt_i32_e32 vcc, v14, v8
	v_lshlrev_b32_e32 v11, 2, v11
	v_lshlrev_b32_e32 v13, 2, v13
	v_cndmask_b32_e32 v8, v215, v14, vcc
	v_lshlrev_b32_e32 v23, 2, v8
	v_and_b32_e32 v8, 7, v80
	v_lshlrev_b32_e32 v8, 4, v8
	v_lshl_add_u64 v[14:15], s[10:11], 0, v[8:9]
	v_lshlrev_b32_e32 v8, 7, v79
	v_lshl_add_u32 v8, s4, 9, v8
	s_lshl_b32 s10, s39, 9
	s_mov_b64 s[8:9], 0
	v_mov_b32_e32 v24, v10
	s_branch .LBB0_2168

; __device__ __forceinline__ void wjob_run(const float* jsrc, bf16_t* jdst, int jsrcld, int jsrccol0, int jncols, int jnrows, int jr0, ...
;     ...
;   const int tn = (j.nrows + 31) >> 5, tk = j.kjob >> 5;
;   for (int t = bid; t < tn * tk; t += nb) {
;     const int n0 = (t / tk) * 32, k0 = (t % tk) * 32;
;     {
;       const int tx = tid & 31, ty = tid >> 5;
;       const int n = n0 + tx;
;       int sc = -1;
;       if (n < j.ncols) {
;         if (j.perm) { int q = n >> 5, i = n & 31; sc = (i < 16) ? (q * 16 + i) : (DFF + q * 16 + i - 16); }
;         else sc = j.srccol0 + n;
;       }
; #pragma unroll
;       for (int i = 0; i < 4; i++) {
;         const int k = k0 + ty + 8 * i;
;         float v = 0.f;
;         if (sc >= 0 && k < j.ksrc) {
;           v = j.src[(size_t)k * j.srcld + sc];
;           if (j.smode == 1) v *= j.mu[k]; else if (j.smode == 2) v *= (1.f - j.mu[k]);
;         }
;         tile[(ty + 8 * i) * 33 + tx] = v;
;       }
;     }
;     __syncthreads();
;     {
;       const int kx = tid & 31, ny = tid >> 5;
; #pragma unroll
;       for (int i = 0; i < 4; i++) {
;         const int n = n0 + ny + 8 * i;
;         if (n < j.nrows) j.dst[(size_t)(j.r0 + n) * j.dstld + j.dstk0 + k0 + kx] = f2bf(tile[kx * 33 + ny + 8 * i]);
; __device__ __forceinline__ void prep_weights(const Params& p, int layer, int which, float* tile, int bid, int nb) {
;     ...
;     wjob_run(win, din, 5632, 0, 5632, 5632, 0, 1024, 0, 1024, 1024, 1, 0, nullptr, tile, bid, nb);
;     wjob_run(wout, dout, 1024, 0, 1024, 1024, 0, 2816, 0, 2816, 2816, 0, 0, nullptr, tile, bid, nb);
;   }
;   if (!(which & 4)) return;
;   if (layer == 0) {
;     bf16_t* d = wb + W0_HIN;
;     const float* s = p.hyb_w_in;
;     wjob_run(s, d, 3600, 0, 1536, 1536, 0, 1024, 0, 1024, 1024, 0, 0, nullptr, tile, bid, nb);
;     wjob_run(s, d, 3600, 1544, 1536, 1536, 1536, 1024, 0, 1024, 1024, 0, 0, nullptr, tile, bid, nb);
;     wjob_run(s, d, 3600, 3088, 512, 512, 3072, 1024, 0, 1024, 1024, 0, 0, nullptr, tile, bid, nb);
;     wjob_run(s, d, 3600, 1536, 8, 8, 3584, 1024, 0, 1024, 1024, 0, 0, nullptr, tile, bid, nb);
;     wjob_run(s, d, 3600, 3080, 8, 120, 3592, 1024, 0, 1024, 1024, 0, 0, nullptr, tile, bid, nb);
;     wjob_run(p.hyb_w_out, wb + W0_HOUT, 1024, 0, 1024, 1024, 0, 1024, 0, 1024, 1024, 0, 0, nullptr, tile, bid, nb);
.LBB0_2655:
	s_and_b64 vcc, exec, s[0:1]
	s_cbranch_vccz .LBB0_2890
	v_readlane_b32 s2, v244, 27
	v_lshrrev_b32_e32 v32, 6, v2
	v_and_b32_e32 v33, 63, v2
	v_readlane_b32 s6, v247, 3
	v_readlane_b32 s7, v247, 4
	v_readfirstlane_b32 s4, v32
	s_lshl_b32 s2, s2, 2
	s_add_i32 s2, s2, s4
	s_lshl_b32 s5, s39, 2
	s_add_u32 s6, s6, 0x8200000
	s_addc_u32 s7, s7, 0
.Lwp_tile:
	s_cmp_ge_u32 s2, 0x1500
	s_cbranch_scc1 .Lwp_done
	s_cmp_ge_u32 s2, 0x1400
	s_cbranch_scc0 .Lwp_j6
	s_mov_b32 s10, s68
	s_mov_b32 s11, s69
	s_sub_u32 s8, s2, 0x1400
	s_movk_i32 s12, 0x1000
	s_mov_b32 s13, 0
	s_mov_b32 s14, 0
	s_add_u32 s16, s6, 0x2840000
	s_addc_u32 s17, s7, 0
	s_movk_i32 s18, 0x800
	s_movk_i32 s19, 0x0
	s_mov_b32 s20, 16
	s_branch .Lwp_go
.Lwp_j6:
	s_cmp_ge_u32 s2, 0x1380
	s_cbranch_scc0 .Lwp_j5
	v_readlane_b32 s10, v246, 43
	v_readlane_b32 s11, v246, 44
	s_sub_u32 s8, s2, 0x1380
	s_movk_i32 s12, 0x3840
	s_mov_b32 s13, 3088
	s_mov_b32 s14, 0
	s_add_u32 s16, s6, 0x2100000
	s_addc_u32 s17, s7, 0
	s_movk_i32 s18, 0x800
	s_movk_i32 s19, 0xc00
	s_mov_b32 s20, 16
	s_branch .Lwp_go
.Lwp_j5:
	s_cmp_ge_u32 s2, 0x1200
	s_cbranch_scc0 .Lwp_j4
	v_readlane_b32 s10, v246, 43
	v_readlane_b32 s11, v246, 44
	s_sub_u32 s8, s2, 0x1200
	s_movk_i32 s12, 0x3840
	s_mov_b32 s13, 1544
	s_mov_b32 s14, 0
	s_add_u32 s16, s6, 0x2100000
	s_addc_u32 s17, s7, 0
	s_movk_i32 s18, 0x800
	s_movk_i32 s19, 0x600
	s_mov_b32 s20, 16
	s_branch .Lwp_go
.Lwp_j4:
	s_cmp_ge_u32 s2, 0x1080
	s_cbranch_scc0 .Lwp_j3
	v_readlane_b32 s10, v246, 43
	v_readlane_b32 s11, v246, 44
	s_sub_u32 s8, s2, 0x1080
	s_movk_i32 s12, 0x3840
	s_mov_b32 s13, 0
	s_mov_b32 s14, 0
	s_add_u32 s16, s6, 0x2100000
	s_addc_u32 s17, s7, 0
	s_movk_i32 s18, 0x800
	s_movk_i32 s19, 0x0
	s_mov_b32 s20, 16
	s_branch .Lwp_go
.Lwp_j3:
	s_cmp_ge_u32 s2, 0xdc0
	s_cbranch_scc0 .Lwp_j2
	v_readlane_b32 s10, v246, 39
	v_readlane_b32 s11, v246, 40
	s_add_u32 s10, s10, 0xb00000
	s_addc_u32 s11, s11, 0
	s_sub_u32 s8, s2, 0xdc0
	s_movk_i32 s12, 0x1000
	s_mov_b32 s13, 0
	s_mov_b32 s14, 0
	s_add_u32 s16, s6, 0x1b80000
	s_addc_u32 s17, s7, 0
	s_movk_i32 s18, 0x1600
	s_movk_i32 s19, 0x0
	s_mov_b32 s20, 44
	s_branch .Lwp_go
.Lwp_j2:
	s_cmp_ge_u32 s2, 0x840
	s_cbranch_scc0 .Lwp_j1
	v_readlane_b32 s10, v246, 37
	v_readlane_b32 s11, v246, 38
	s_add_u32 s10, s10, 0x1600000
	s_addc_u32 s11, s11, 0
	s_sub_u32 s8, s2, 0x840
	s_movk_i32 s12, 0x5800
	s_mov_b32 s13, 0
	s_mov_b32 s14, 1
	s_add_u32 s16, s6, 0x1080000
	s_addc_u32 s17, s7, 0
	s_movk_i32 s18, 0x800
	s_movk_i32 s19, 0x0
	s_mov_b32 s20, 16
	s_branch .Lwp_go
.Lwp_j1:
	s_cmp_ge_u32 s2, 0x580
	s_cbranch_scc0 .Lwp_j0
	v_readlane_b32 s10, v246, 39
	v_readlane_b32 s11, v246, 40
	s_sub_u32 s8, s2, 0x580
	s_movk_i32 s12, 0x1000
	s_mov_b32 s13, 0
	s_mov_b32 s14, 0
	s_add_u32 s16, s6, 0xb00000
	s_addc_u32 s17, s7, 0
	s_movk_i32 s18, 0x1600
	s_movk_i32 s19, 0x0
	s_mov_b32 s20, 44
	s_branch .Lwp_go
.Lwp_j0:
	v_readlane_b32 s10, v246, 37
	v_readlane_b32 s11, v246, 38
	s_mov_b32 s8, s2
	s_movk_i32 s12, 0x5800
	s_mov_b32 s13, 0
	s_mov_b32 s14, 1
	s_add_u32 s16, s6, 0x0
	s_addc_u32 s17, s7, 0
	s_movk_i32 s18, 0x800
	s_movk_i32 s19, 0x0
	s_mov_b32 s20, 16
	s_branch .Lwp_go
.Lwp_go:
	s_cmp_eq_u32 s20, 16
	s_cbranch_scc1 .Lwp_tk16
	s_mul_i32 s21, s8, 0x2e9
	s_lshr_b32 s21, s21, 15
	s_branch .Lwp_tkj
.Lwp_tk16:
	s_lshr_b32 s21, s8, 4
.Lwp_tkj:
	s_mul_i32 s22, s21, s20
	s_sub_u32 s9, s8, s22
	s_lshl_b32 s21, s21, 6
	s_lshl_b32 s9, s9, 6
	v_add_u32_e32 v36, s21, v33
	s_cmp_eq_u32 s14, 0
	s_cbranch_scc1 .Lwp_lin
	v_lshrrev_b32_e32 v37, 5, v36
	v_lshlrev_b32_e32 v37, 4, v37
	v_and_b32_e32 v34, 15, v36
	v_add_u32_e32 v34, v34, v37
	v_bfe_u32 v37, v36, 4, 1
	v_mul_u32_u24_e32 v37, 0xb00, v37
	v_add_u32_e32 v34, v34, v37
	s_branch .Lwp_col
.Lwp_lin:
	v_add_u32_e32 v34, s13, v36
.Lwp_col:
	v_lshlrev_b32_e32 v34, 2, v34
	s_mul_i32 s22, s9, s12
	s_mul_hi_u32 s23, s9, s12
	s_add_u32 s22, s10, s22
	s_addc_u32 s23, s11, s23
	v_add_u32_e32 v36, s19, v36
	v_mul_lo_u32 v35, v36, s18
	s_lshl_b32 s9, s9, 1
	v_add_u32_e32 v35, s9, v35
	global_load_dword v40, v34, s[22:23]
	s_add_u32 s22, s22, s12
	s_addc_u32 s23, s23, 0
	global_load_dword v41, v34, s[22:23]
	s_add_u32 s22, s22, s12
	s_addc_u32 s23, s23, 0
	global_load_dword v42, v34, s[22:23]
	s_add_u32 s22, s22, s12
	s_addc_u32 s23, s23, 0
	global_load_dword v43, v34, s[22:23]
	s_add_u32 s22, s22, s12
	s_addc_u32 s23, s23, 0
	global_load_dword v44, v34, s[22:23]
	s_add_u32 s22, s22, s12
	s_addc_u32 s23, s23, 0
	global_load_dword v45, v34, s[22:23]
	s_add_u32 s22, s22, s12
	s_addc_u32 s23, s23, 0
	global_load_dword v46, v34, s[22:23]
	s_add_u32 s22, s22, s12
	s_addc_u32 s23, s23, 0
	global_load_dword v47, v34, s[22:23]
	s_add_u32 s22, s22, s12
	s_addc_u32 s23, s23, 0
	global_load_dword v48, v34, s[22:23]
	s_add_u32 s22, s22, s12
	s_addc_u32 s23, s23, 0
	global_load_dword v49, v34, s[22:23]
	s_add_u32 s22, s22, s12
	s_addc_u32 s23, s23, 0
	global_load_dword v50, v34, s[22:23]
	s_add_u32 s22, s22, s12
	s_addc_u32 s23, s23, 0
	global_load_dword v51, v34, s[22:23]
	s_add_u32 s22, s22, s12
	s_addc_u32 s23, s23, 0
	global_load_dword v52, v34, s[22:23]
	s_add_u32 s22, s22, s12
	s_addc_u32 s23, s23, 0
	global_load_dword v53, v34, s[22:23]
	s_add_u32 s22, s22, s12
	s_addc_u32 s23, s23, 0
	global_load_dword v54, v34, s[22:23]
	s_add_u32 s22, s22, s12
	s_addc_u32 s23, s23, 0
	global_load_dword v55, v34, s[22:23]
	s_add_u32 s22, s22, s12
	s_addc_u32 s23, s23, 0
	global_load_dword v56, v34, s[22:23]
	s_add_u32 s22, s22, s12
	s_addc_u32 s23, s23, 0
	global_load_dword v57, v34, s[22:23]
	s_add_u32 s22, s22, s12
	s_addc_u32 s23, s23, 0
	global_load_dword v58, v34, s[22:23]
	s_add_u32 s22, s22, s12
; __device__ __forceinline__ void wjob_run(const float* jsrc, bf16_t* jdst, int jsrcld, int jsrccol0, int jncols, int jnrows, int jr0, ...
;     ...
;       for (int i = 0; i < 4; i++) {
;         const int k = k0 + ty + 8 * i;
;         float v = 0.f;
;         if (sc >= 0 && k < j.ksrc) {
;           v = j.src[(size_t)k * j.srcld + sc];
;           if (j.smode == 1) v *= j.mu[k]; else if (j.smode == 2) v *= (1.f - j.mu[k]);
;         }
;         tile[(ty + 8 * i) * 33 + tx] = v;
;       }
;     }
;     __syncthreads();
;     {
;       const int kx = tid & 31, ny = tid >> 5;
; #pragma unroll
;       for (int i = 0; i < 4; i++) {
;         const int n = n0 + ny + 8 * i;
;         if (n < j.nrows) j.dst[(size_t)(j.r0 + n) * j.dstld + j.dstk0 + k0 + kx] = f2bf(tile[kx * 33 + ny + 8 * i]);
; __device__ __forceinline__ void prep_weights(const Params& p, int layer, int which, float* tile, int bid, int nb) {
;     ...
;     wjob_run(win, din, 5632, 0, 5632, 5632, 0, 1024, 0, 1024, 1024, 1, 0, nullptr, tile, bid, nb);
;     wjob_run(wout, dout, 1024, 0, 1024, 1024, 0, 2816, 0, 2816, 2816, 0, 0, nullptr, tile, bid, nb);
	s_addc_u32 s23, s23, 0
	global_load_dword v59, v34, s[22:23]
	s_add_u32 s22, s22, s12
	s_addc_u32 s23, s23, 0
	global_load_dword v60, v34, s[22:23]
	s_add_u32 s22, s22, s12
	s_addc_u32 s23, s23, 0
	global_load_dword v61, v34, s[22:23]
	s_add_u32 s22, s22, s12
	s_addc_u32 s23, s23, 0
	global_load_dword v62, v34, s[22:23]
	s_add_u32 s22, s22, s12
	s_addc_u32 s23, s23, 0
	global_load_dword v63, v34, s[22:23]
	s_add_u32 s22, s22, s12
	s_addc_u32 s23, s23, 0
	global_load_dword v64, v34, s[22:23]
	s_add_u32 s22, s22, s12
	s_addc_u32 s23, s23, 0
	global_load_dword v65, v34, s[22:23]
	s_add_u32 s22, s22, s12
	s_addc_u32 s23, s23, 0
	global_load_dword v66, v34, s[22:23]
	s_add_u32 s22, s22, s12
	s_addc_u32 s23, s23, 0
	global_load_dword v67, v34, s[22:23]
	s_add_u32 s22, s22, s12
	s_addc_u32 s23, s23, 0
	global_load_dword v68, v34, s[22:23]
	s_add_u32 s22, s22, s12
	s_addc_u32 s23, s23, 0
	global_load_dword v69, v34, s[22:23]
	s_add_u32 s22, s22, s12
	s_addc_u32 s23, s23, 0
	global_load_dword v70, v34, s[22:23]
	s_add_u32 s22, s22, s12
	s_addc_u32 s23, s23, 0
	global_load_dword v71, v34, s[22:23]
	s_add_u32 s22, s22, s12
	s_addc_u32 s23, s23, 0
	global_load_dword v72, v34, s[22:23]
	s_add_u32 s22, s22, s12
	s_addc_u32 s23, s23, 0
	global_load_dword v73, v34, s[22:23]
	s_add_u32 s22, s22, s12
	s_addc_u32 s23, s23, 0
	global_load_dword v74, v34, s[22:23]
	s_add_u32 s22, s22, s12
	s_addc_u32 s23, s23, 0
	global_load_dword v75, v34, s[22:23]
	s_add_u32 s22, s22, s12
	s_addc_u32 s23, s23, 0
	global_load_dword v76, v34, s[22:23]
	s_add_u32 s22, s22, s12
	s_addc_u32 s23, s23, 0
	global_load_dword v77, v34, s[22:23]
	s_add_u32 s22, s22, s12
	s_addc_u32 s23, s23, 0
	global_load_dword v78, v34, s[22:23]
	s_add_u32 s22, s22, s12
	s_addc_u32 s23, s23, 0
	global_load_dword v79, v34, s[22:23]
	s_add_u32 s22, s22, s12
	s_addc_u32 s23, s23, 0
	global_load_dword v80, v34, s[22:23]
	s_add_u32 s22, s22, s12
	s_addc_u32 s23, s23, 0
	global_load_dword v81, v34, s[22:23]
	s_add_u32 s22, s22, s12
	s_addc_u32 s23, s23, 0
	global_load_dword v82, v34, s[22:23]
	s_add_u32 s22, s22, s12
	s_addc_u32 s23, s23, 0
	global_load_dword v83, v34, s[22:23]
	s_add_u32 s22, s22, s12
	s_addc_u32 s23, s23, 0
	global_load_dword v84, v34, s[22:23]
	s_add_u32 s22, s22, s12
	s_addc_u32 s23, s23, 0
	global_load_dword v85, v34, s[22:23]
	s_add_u32 s22, s22, s12
	s_addc_u32 s23, s23, 0
	global_load_dword v86, v34, s[22:23]
	s_add_u32 s22, s22, s12
	s_addc_u32 s23, s23, 0
	global_load_dword v87, v34, s[22:23]
	s_add_u32 s22, s22, s12
	s_addc_u32 s23, s23, 0
	global_load_dword v88, v34, s[22:23]
	s_add_u32 s22, s22, s12
	s_addc_u32 s23, s23, 0
	global_load_dword v89, v34, s[22:23]
	s_add_u32 s22, s22, s12
	s_addc_u32 s23, s23, 0
	global_load_dword v90, v34, s[22:23]
	s_add_u32 s22, s22, s12
	s_addc_u32 s23, s23, 0
	global_load_dword v91, v34, s[22:23]
	s_add_u32 s22, s22, s12
	s_addc_u32 s23, s23, 0
	global_load_dword v92, v34, s[22:23]
	s_add_u32 s22, s22, s12
	s_addc_u32 s23, s23, 0
	global_load_dword v93, v34, s[22:23]
	s_add_u32 s22, s22, s12
	s_addc_u32 s23, s23, 0
	global_load_dword v94, v34, s[22:23]
	s_add_u32 s22, s22, s12
	s_addc_u32 s23, s23, 0
	global_load_dword v95, v34, s[22:23]
	s_add_u32 s22, s22, s12
	s_addc_u32 s23, s23, 0
	global_load_dword v96, v34, s[22:23]
	s_add_u32 s22, s22, s12
	s_addc_u32 s23, s23, 0
	global_load_dword v97, v34, s[22:23]
	s_add_u32 s22, s22, s12
	s_addc_u32 s23, s23, 0
	global_load_dword v98, v34, s[22:23]
	s_add_u32 s22, s22, s12
	s_addc_u32 s23, s23, 0
	global_load_dword v99, v34, s[22:23]
	s_add_u32 s22, s22, s12
	s_addc_u32 s23, s23, 0
	global_load_dword v100, v34, s[22:23]
	s_add_u32 s22, s22, s12
	s_addc_u32 s23, s23, 0
	global_load_dword v101, v34, s[22:23]
	s_add_u32 s22, s22, s12
	s_addc_u32 s23, s23, 0
	global_load_dword v102, v34, s[22:23]
	s_add_u32 s22, s22, s12
	s_addc_u32 s23, s23, 0
	global_load_dword v103, v34, s[22:23]
	s_add_u32 s22, s22, s12
	s_addc_u32 s23, s23, 0
	s_waitcnt vmcnt(0)
	v_cvt_pk_bf16_f32 v104, v40, v41
	v_cvt_pk_bf16_f32 v105, v42, v43
	v_cvt_pk_bf16_f32 v106, v44, v45
	v_cvt_pk_bf16_f32 v107, v46, v47
	v_cvt_pk_bf16_f32 v108, v48, v49
	v_cvt_pk_bf16_f32 v109, v50, v51
	v_cvt_pk_bf16_f32 v110, v52, v53
	v_cvt_pk_bf16_f32 v111, v54, v55
	v_cvt_pk_bf16_f32 v112, v56, v57
	v_cvt_pk_bf16_f32 v113, v58, v59
	v_cvt_pk_bf16_f32 v114, v60, v61
	v_cvt_pk_bf16_f32 v115, v62, v63
	v_cvt_pk_bf16_f32 v116, v64, v65
	v_cvt_pk_bf16_f32 v117, v66, v67
	v_cvt_pk_bf16_f32 v118, v68, v69
	v_cvt_pk_bf16_f32 v119, v70, v71
	v_cvt_pk_bf16_f32 v120, v72, v73
	v_cvt_pk_bf16_f32 v121, v74, v75
	v_cvt_pk_bf16_f32 v122, v76, v77
	v_cvt_pk_bf16_f32 v123, v78, v79
	v_cvt_pk_bf16_f32 v124, v80, v81
	v_cvt_pk_bf16_f32 v125, v82, v83
	v_cvt_pk_bf16_f32 v126, v84, v85
	v_cvt_pk_bf16_f32 v127, v86, v87
	v_cvt_pk_bf16_f32 v128, v88, v89
	v_cvt_pk_bf16_f32 v129, v90, v91
	v_cvt_pk_bf16_f32 v130, v92, v93
	v_cvt_pk_bf16_f32 v131, v94, v95
	v_cvt_pk_bf16_f32 v132, v96, v97
	v_cvt_pk_bf16_f32 v133, v98, v99
	v_cvt_pk_bf16_f32 v134, v100, v101
	v_cvt_pk_bf16_f32 v135, v102, v103
	global_store_dwordx4 v35, v[104:107], s[16:17]
	global_store_dwordx4 v35, v[108:111], s[16:17] offset:16
	global_store_dwordx4 v35, v[112:115], s[16:17] offset:32
	global_store_dwordx4 v35, v[116:119], s[16:17] offset:48
	global_store_dwordx4 v35, v[120:123], s[16:17] offset:64
	global_store_dwordx4 v35, v[124:127], s[16:17] offset:80
	global_store_dwordx4 v35, v[128:131], s[16:17] offset:96
	global_store_dwordx4 v35, v[132:135], s[16:17] offset:112
	s_add_i32 s2, s2, s5
	s_branch .Lwp_tile
.Lwp_done:
	v_readlane_b32 s0, v244, 27
	s_cmpk_lt_i32 s0, 0x1600
	s_cselect_b64 s[4:5], -1, 0
	s_cmpk_gt_i32 s0, 0x15ff
	v_mov_b32_e32 v8, v2
	s_branch .LBB0_2681
	v_and_b32_e32 v16, 31, v8
	v_readlane_b32 s0, v247, 23
	s_waitcnt lgkmcnt(1)
	v_ashrrev_i32_e32 v17, 5, v8
	v_lshlrev_b32_e32 v8, 1, v16
	v_readlane_b32 s1, v247, 24
	s_waitcnt lgkmcnt(0)
	v_lshlrev_b32_e32 v12, 2, v16
	v_lshlrev_b32_e32 v13, 2, v17
	s_waitcnt vmcnt(0)
	v_lshl_add_u64 v[10:11], s[0:1], 0, v[8:9]
	s_movk_i32 s0, 0x84
	v_mul_u32_u24_e32 v14, 0x84, v16
	v_mul_lo_u32 v8, v17, s0
	v_readlane_b32 s11, v244, 27
	v_cmp_lt_u32_e64 s[6:7], 15, v16
	v_add_u32_e32 v18, 0xaf0, v16
	s_lshl_b32 s2, s11, 5
	s_lshl_b32 s10, s39, 5
	v_add_u32_e32 v19, v12, v8
	v_add_u32_e32 v20, v13, v14
	s_branch .LBB0_2659

; __device__ __forceinline__ int otid() { int t = threadIdx.x; asm volatile("" : "+v"(t)); return t; }
; __device__ __forceinline__ void wjob_run(const float* jsrc, bf16_t* jdst, int jsrcld, int jsrccol0, int jncols, int jnrows, int jr0, ...
;     ...
;   const int tid = otid();
;   const int tn = (j.nrows + 31) >> 5, tk = j.kjob >> 5;
;   for (int t = bid; t < tn * tk; t += nb) {
;     const int n0 = (t / tk) * 32, k0 = (t % tk) * 32;
;     {
;       const int tx = tid & 31, ty = tid >> 5;
;       const int n = n0 + tx;
;       int sc = -1;
;       if (n < j.ncols) {
;         if (j.perm) { int q = n >> 5, i = n & 31; sc = (i < 16) ? (q * 16 + i) : (DFF + q * 16 + i - 16); }
; __device__ __forceinline__ void prep_weights(const Params& p, int layer, int which, float* tile, int bid, int nb) {
;     ...
;     wjob_run(wout, dout, 1024, 0, 1024, 1024, 0, 2816, 0, 2816, 2816, 0, 0, nullptr, tile, bid, nb);
.LBB0_2681:
	v_readlane_b32 s0, v244, 27
	s_cmpk_lt_i32 s0, 0xb00
	s_cselect_b64 s[8:9], -1, 0
	s_cmpk_gt_i32 s0, 0xaff
	v_mov_b32_e32 v8, v2
	s_branch .LBB0_2700
	v_and_b32_e32 v16, 31, v8
	v_readlane_b32 s0, v247, 39
	s_waitcnt lgkmcnt(1)
	v_ashrrev_i32_e32 v17, 5, v8
	v_lshlrev_b32_e32 v8, 1, v16
	v_readlane_b32 s1, v247, 40
	s_waitcnt lgkmcnt(0)
	v_lshlrev_b32_e32 v12, 2, v16
	v_lshlrev_b32_e32 v13, 2, v17
	s_waitcnt vmcnt(0)
	v_lshl_add_u64 v[10:11], s[0:1], 0, v[8:9]
	s_movk_i32 s0, 0x84
	v_mul_u32_u24_e32 v14, 0x84, v16
	v_mul_lo_u32 v8, v17, s0
	v_readlane_b32 s11, v244, 27
	s_lshl_b32 s2, s11, 5
	s_lshl_b32 s10, s39, 5
	v_add_u32_e32 v18, v12, v8
	v_add_u32_e32 v19, v13, v14
	s_branch .LBB0_2684

; __device__ __forceinline__ int otid() { int t = threadIdx.x; asm volatile("" : "+v"(t)); return t; }
; __device__ __forceinline__ void wjob_run(const float* jsrc, bf16_t* jdst, int jsrcld, int jsrccol0, int jncols, int jnrows, int jr0, ...
;     ...
;   const int tid = otid();
;   const int tn = (j.nrows + 31) >> 5, tk = j.kjob >> 5;
;   for (int t = bid; t < tn * tk; t += nb) {
;     const int n0 = (t / tk) * 32, k0 = (t % tk) * 32;
;     {
;       const int tx = tid & 31, ty = tid >> 5;
;       const int n = n0 + tx;
;       int sc = -1;
;       if (n < j.ncols) {
;         if (j.perm) { int q = n >> 5, i = n & 31; sc = (i < 16) ? (q * 16 + i) : (DFF + q * 16 + i - 16); }
; __device__ __forceinline__ void prep_weights(const Params& p, int layer, int which, float* tile, int bid, int nb) {
;     ...
;     wjob_run(win, din, 5632, 0, 5632, 5632, 0, 1024, 0, 1024, 1024, 1, 0, nullptr, tile, bid, nb);
.LBB0_2700:
	v_mov_b32_e32 v8, v2
	s_andn2_b64 vcc, exec, s[4:5]
	s_branch .LBB0_2725
	v_and_b32_e32 v16, 31, v8
	v_readlane_b32 s0, v247, 31
	s_waitcnt lgkmcnt(1)
	v_ashrrev_i32_e32 v17, 5, v8
	v_lshlrev_b32_e32 v8, 1, v16
	v_readlane_b32 s1, v247, 32
	s_waitcnt lgkmcnt(0)
	v_lshlrev_b32_e32 v12, 2, v16
	v_lshlrev_b32_e32 v13, 2, v17
	s_waitcnt vmcnt(0)
	v_lshl_add_u64 v[10:11], s[0:1], 0, v[8:9]
	s_movk_i32 s0, 0x84
	v_mul_u32_u24_e32 v14, 0x84, v16
	v_mul_lo_u32 v8, v17, s0
	v_readlane_b32 s11, v244, 27
	v_cmp_lt_u32_e64 s[6:7], 15, v16
	v_add_u32_e32 v18, 0xaf0, v16
	s_lshl_b32 s2, s11, 5
	s_lshl_b32 s10, s39, 5
	v_add_u32_e32 v19, v12, v8
	v_add_u32_e32 v20, v13, v14
	s_branch .LBB0_2703

; __device__ __forceinline__ int otid() { int t = threadIdx.x; asm volatile("" : "+v"(t)); return t; }
; __device__ __forceinline__ void wjob_run(const float* jsrc, bf16_t* jdst, int jsrcld, int jsrccol0, int jncols, int jnrows, int jr0, ...
;     ...
;   const int tid = otid();
;   const int tn = (j.nrows + 31) >> 5, tk = j.kjob >> 5;
;   for (int t = bid; t < tn * tk; t += nb) {
;     const int n0 = (t / tk) * 32, k0 = (t % tk) * 32;
;     {
;       const int tx = tid & 31, ty = tid >> 5;
;       const int n = n0 + tx;
;       int sc = -1;
;       if (n < j.ncols) {
;         if (j.perm) { int q = n >> 5, i = n & 31; sc = (i < 16) ? (q * 16 + i) : (DFF + q * 16 + i - 16); }
; __device__ __forceinline__ void prep_weights(const Params& p, int layer, int which, float* tile, int bid, int nb) {
;     ...
;     wjob_run(wout, dout, 1024, 0, 1024, 1024, 0, 2816, 0, 2816, 2816, 0, 0, nullptr, tile, bid, nb);
.LBB0_2725:
	v_mov_b32_e32 v8, v2
	s_andn2_b64 vcc, exec, s[8:9]
	s_branch .LBB0_2744
	v_and_b32_e32 v16, 31, v8
	v_readlane_b32 s0, v247, 29
	s_waitcnt lgkmcnt(1)
	v_ashrrev_i32_e32 v17, 5, v8
	v_lshlrev_b32_e32 v8, 1, v16
	v_readlane_b32 s1, v247, 30
	s_waitcnt lgkmcnt(0)
	v_lshlrev_b32_e32 v12, 2, v16
	v_lshlrev_b32_e32 v13, 2, v17
	s_waitcnt vmcnt(0)
	v_lshl_add_u64 v[10:11], s[0:1], 0, v[8:9]
	s_movk_i32 s0, 0x84
	v_mul_u32_u24_e32 v14, 0x84, v16
	v_mul_lo_u32 v8, v17, s0
	v_readlane_b32 s7, v244, 27
	s_lshl_b32 s2, s7, 5
	s_lshl_b32 s6, s39, 5
	v_add_u32_e32 v18, v12, v8
	v_add_u32_e32 v19, v13, v14
	s_branch .LBB0_2728

; __device__ __forceinline__ int otid() { int t = threadIdx.x; asm volatile("" : "+v"(t)); return t; }
; __device__ __forceinline__ void wjob_run(const float* jsrc, bf16_t* jdst, int jsrcld, int jsrccol0, int jncols, int jnrows, int jr0, ...
;     ...
;   const int tid = otid();
;   const int tn = (j.nrows + 31) >> 5, tk = j.kjob >> 5;
;   for (int t = bid; t < tn * tk; t += nb) {
;     const int n0 = (t / tk) * 32, k0 = (t % tk) * 32;
;     {
;       const int tx = tid & 31, ty = tid >> 5;
;       const int n = n0 + tx;
;       int sc = -1;
;       if (n < j.ncols) {
;         if (j.perm) { int q = n >> 5, i = n & 31; sc = (i < 16) ? (q * 16 + i) : (DFF + q * 16 + i - 16); }
; __device__ __forceinline__ void prep_weights(const Params& p, int layer, int which, float* tile, int bid, int nb) {
;     ...
;     wjob_run(s, d, 3600, 0, 1536, 1536, 0, 1024, 0, 1024, 1024, 0, 0, nullptr, tile, bid, nb);
.LBB0_2744:
	v_readlane_b32 s0, v244, 27
	s_cmpk_lt_i32 s0, 0x600
	v_mov_b32_e32 v8, v2
	s_cselect_b64 s[4:5], -1, 0
	s_cmpk_gt_i32 s0, 0x5ff
	s_branch .LBB0_2763
	v_and_b32_e32 v16, 31, v8
	v_readlane_b32 s0, v246, 27
	s_waitcnt lgkmcnt(1)
	v_ashrrev_i32_e32 v17, 5, v8
	v_lshlrev_b32_e32 v8, 1, v16
	v_readlane_b32 s1, v246, 28
	s_waitcnt lgkmcnt(0)
	v_lshlrev_b32_e32 v12, 2, v16
	v_lshlrev_b32_e32 v13, 2, v17
	s_waitcnt vmcnt(0)
	v_lshl_add_u64 v[10:11], s[0:1], 0, v[8:9]
	s_movk_i32 s0, 0x84
	v_mul_u32_u24_e32 v14, 0x84, v16
	v_mul_lo_u32 v8, v17, s0
	v_readlane_b32 s7, v244, 27
	s_lshl_b32 s2, s7, 5
	s_lshl_b32 s6, s39, 5
	v_add_u32_e32 v18, v12, v8
	v_add_u32_e32 v19, v13, v14
	s_branch .LBB0_2747

; __device__ __forceinline__ int otid() { int t = threadIdx.x; asm volatile("" : "+v"(t)); return t; }
; __device__ __forceinline__ void wjob_run(const float* jsrc, bf16_t* jdst, int jsrcld, int jsrccol0, int jncols, int jnrows, int jr0, ...
;     ...
;   const int tid = otid();
;   const int tn = (j.nrows + 31) >> 5, tk = j.kjob >> 5;
;   for (int t = bid; t < tn * tk; t += nb) {
;     const int n0 = (t / tk) * 32, k0 = (t % tk) * 32;
;     {
;       const int tx = tid & 31, ty = tid >> 5;
;       const int n = n0 + tx;
;       int sc = -1;
;       if (n < j.ncols) {
;         if (j.perm) { int q = n >> 5, i = n & 31; sc = (i < 16) ? (q * 16 + i) : (DFF + q * 16 + i - 16); }
; __device__ __forceinline__ void prep_weights(const Params& p, int layer, int which, float* tile, int bid, int nb) {
;     ...
;     wjob_run(s, d, 3600, 1544, 1536, 1536, 1536, 1024, 0, 1024, 1024, 0, 0, nullptr, tile, bid, nb);
.LBB0_2763:
	v_mov_b32_e32 v8, v2
	s_andn2_b64 vcc, exec, s[4:5]
	s_branch .LBB0_2782
	v_and_b32_e32 v16, 31, v8
	v_readlane_b32 s0, v246, 27
	s_waitcnt lgkmcnt(1)
	v_ashrrev_i32_e32 v17, 5, v8
	v_lshlrev_b32_e32 v8, 1, v16
	v_readlane_b32 s1, v246, 28
	s_waitcnt lgkmcnt(0)
	v_lshlrev_b32_e32 v12, 2, v16
	v_lshlrev_b32_e32 v13, 2, v17
	s_waitcnt vmcnt(0)
	v_lshl_add_u64 v[10:11], s[0:1], 0, v[8:9]
	s_movk_i32 s0, 0x84
	v_mul_u32_u24_e32 v14, 0x84, v16
	v_mul_lo_u32 v8, v17, s0
	v_readlane_b32 s5, v244, 27
	s_lshl_b32 s2, s5, 5
	s_lshl_b32 s4, s39, 5
	v_add_u32_e32 v18, v12, v8
	v_add_u32_e32 v19, v13, v14
	s_branch .LBB0_2766

; __device__ __forceinline__ int otid() { int t = threadIdx.x; asm volatile("" : "+v"(t)); return t; }
; __device__ __forceinline__ void wjob_run(const float* jsrc, bf16_t* jdst, int jsrcld, int jsrccol0, int jncols, int jnrows, int jr0, ...
;     ...
;   const int tid = otid();
;   const int tn = (j.nrows + 31) >> 5, tk = j.kjob >> 5;
;   for (int t = bid; t < tn * tk; t += nb) {
;     const int n0 = (t / tk) * 32, k0 = (t % tk) * 32;
;     {
;       const int tx = tid & 31, ty = tid >> 5;
;       const int n = n0 + tx;
;       int sc = -1;
;       if (n < j.ncols) {
;         if (j.perm) { int q = n >> 5, i = n & 31; sc = (i < 16) ? (q * 16 + i) : (DFF + q * 16 + i - 16); }
; __device__ __forceinline__ void prep_weights(const Params& p, int layer, int which, float* tile, int bid, int nb) {
;     ...
;     wjob_run(s, d, 3600, 3088, 512, 512, 3072, 1024, 0, 1024, 1024, 0, 0, nullptr, tile, bid, nb);
.LBB0_2782:
	v_readlane_b32 s5, v244, 27
	v_mov_b32_e32 v8, v2
	s_cmpk_gt_i32 s5, 0x1ff
	s_branch .LBB0_2802
	v_and_b32_e32 v16, 31, v8
	v_readlane_b32 s0, v246, 27
	s_waitcnt lgkmcnt(1)
	v_ashrrev_i32_e32 v17, 5, v8
	v_lshlrev_b32_e32 v8, 1, v16
	v_readlane_b32 s1, v246, 28
	s_waitcnt lgkmcnt(0)
	v_lshlrev_b32_e32 v12, 2, v16
	v_lshlrev_b32_e32 v13, 2, v17
	s_waitcnt vmcnt(0)
	v_lshl_add_u64 v[10:11], s[0:1], 0, v[8:9]
	s_movk_i32 s0, 0x84
	v_mul_u32_u24_e32 v14, 0x84, v16
	v_mul_lo_u32 v8, v17, s0
	s_lshl_b32 s2, s5, 5
	s_lshl_b32 s4, s39, 5
	v_add_u32_e32 v18, v12, v8
	v_add_u32_e32 v19, v13, v14
	s_branch .LBB0_2785

; __device__ __forceinline__ int otid() { int t = threadIdx.x; asm volatile("" : "+v"(t)); return t; }
; __device__ __forceinline__ void wjob_run(const float* jsrc, bf16_t* jdst, int jsrcld, int jsrccol0, int jncols, int jnrows, int jr0, ...
;     ...
;   const int tid = otid();
;   const int tn = (j.nrows + 31) >> 5, tk = j.kjob >> 5;
;   for (int t = bid; t < tn * tk; t += nb) {
;     const int n0 = (t / tk) * 32, k0 = (t % tk) * 32;
;     {
;       const int tx = tid & 31, ty = tid >> 5;
;       const int n = n0 + tx;
;       int sc = -1;
;       if (n < j.ncols) {
;         if (j.perm) { int q = n >> 5, i = n & 31; sc = (i < 16) ? (q * 16 + i) : (DFF + q * 16 + i - 16); }
; __device__ __forceinline__ void prep_weights(const Params& p, int layer, int which, float* tile, int bid, int nb) {
;     ...
;     wjob_run(p.hyb_w_out, wb + W0_HOUT, 1024, 0, 1024, 1024, 0, 1024, 0, 1024, 1024, 0, 0, nullptr, tile, bid, nb);
.LBB0_2842:
	v_mov_b32_e32 v8, v2
	s_cmpk_gt_i32 s5, 0x3ff
	s_branch .LBB0_2862
	v_and_b32_e32 v16, 31, v8
	v_readlane_b32 s0, v247, 45
	s_waitcnt lgkmcnt(1)
	v_ashrrev_i32_e32 v17, 5, v8
	v_lshlrev_b32_e32 v8, 1, v16
	v_readlane_b32 s1, v247, 46
	s_waitcnt lgkmcnt(0)
	v_lshlrev_b32_e32 v12, 2, v16
	v_lshlrev_b32_e32 v13, 2, v17
	s_waitcnt vmcnt(0)
	v_lshl_add_u64 v[10:11], s[0:1], 0, v[8:9]
	s_movk_i32 s0, 0x84
	v_mul_u32_u24_e32 v14, 0x84, v16
	v_mul_lo_u32 v8, v17, s0
	s_lshl_b32 s2, s5, 5
	s_lshl_b32 s4, s39, 5
	v_add_u32_e32 v18, v12, v8
	v_add_u32_e32 v19, v13, v14
	s_branch .LBB0_2845
